# mixer A: one static s_setprio 1 for waves 4-7 through the dense attention loop, reset at the phase end
# baseline (speedup 1.0000x reference)
; __device__ __forceinline__ const float* argp(const Frame& F, int idx) { unsigned long long p = F.kargs; asm volatile("" : "+s"(p)); return ((const float* const __attribute__((address_space(4)))*)p)[idx]; }
; template <int MODE> __device__ __forceinline__ void phase_attn_fast(const Frame& F0) {
;   const Frame F = fresh(F0);
;   float nlam = 0.f;
;   if (MODE == 3 || MODE == 2) { const float* lp = argp(F, 16);
;     const float d1 = wave_sum(lp[F.lane] * lp[128 + F.lane] + lp[64 + F.lane] * lp[192 + F.lane]);
;     const float d2 = wave_sum(lp[256 + F.lane] * lp[384 + F.lane] + lp[320 + F.lane] * lp[448 + F.lane]);
;     nlam = -(expf(d1) - expf(d2) + LAM_INIT2); }
;   for (int i = 0;; ++i) {
;     const int it = i * F.G + F.vcu; if (it >= 2560) break;
;     const ItemId d = item_decode(it);
.LBB0_1102:
	v_readlane_b32 s40, v254, 0
	v_readlane_b32 s41, v254, 1
	s_load_dwordx4 s[36:39], s[40:41], 0xd0
	s_ashr_i32 s30, s4, 6
	s_cmp_lt_u32 s30, 4
	s_cbranch_scc1 .Lprio_a_skip
	s_setprio 1
.Lprio_a_skip:
	s_lshl_b32 s4, s7, 3
	s_add_i32 s31, s4, s30
	s_lshl_b32 s46, s6, 3
	s_waitcnt lgkmcnt(0)
	s_add_u32 s4, s38, 0x17100000
	s_addc_u32 s5, s39, 0
	s_add_u32 s42, s38, 0x21400000
	s_addc_u32 s43, s39, 0
	s_add_u32 s8, s38, 0x300000
	s_addc_u32 s9, s39, 0
	s_add_u32 s12, s38, 0x600000
	s_addc_u32 s13, s39, 0
	s_add_u32 s44, s38, 0x3c400000
	s_addc_u32 s45, s39, 0
	s_add_u32 s24, s38, 0x100000
	s_addc_u32 s25, s39, 0
	s_add_u32 s26, s38, 0x900000
	s_addc_u32 s27, s39, 0
	v_and_b32_e32 v0, 63, v181
	s_add_u32 s28, s38, 0x46800000
	s_addc_u32 s29, s39, 0
	s_mov_b64 s[30:31], s[36:37]
	s_cmpk_gt_i32 s7, 0x9ff
	s_cbranch_scc1 .LBB0_1130
	s_add_u32 s38, s38, 0x11000
	s_addc_u32 s39, s39, 0
	s_mov_b32 s8, 0
	s_mov_b32 s9, s7
	s_branch .LBB0_1105

; __device__ __forceinline__ int lane_id() { int l; asm volatile("v_mbcnt_lo_u32_b32 %0, -1, 0\n\tv_mbcnt_hi_u32_b32 %0, -1, %0" : "=v"(l)); return l; }
; __device__ __forceinline__ void xcd_barrier(const XcdBarrier& b) {
;     asm volatile("s_waitcnt vmcnt(0)" ::: "memory");
;     __syncthreads();
;     if (b.w0 == 0u && lane_id() == 0) {
;         unsigned* bar = b.bar;
;         __builtin_amdgcn_s_waitcnt(0);
;         unsigned nloc = b.st[0], nx = b.st[1];
;         if (nloc == 0u) { xcd_barrier_complete(bar, b.x, nloc, nx); b.st[0] = nloc; b.st[1] = nx; }
; template <int MODE> __device__ __forceinline__ void phase_attn_fast(const Frame& F0) {
;     ...
;   for (int i = 0;; ++i) {
;     const int it = i * F.G + F.vcu; if (it >= 2560) break;
.LBB0_1130:
	s_setprio 0
	s_waitcnt vmcnt(0)
	v_readlane_b32 s4, v254, 6
	v_readlane_b32 s5, v254, 7
	s_and_b64 vcc, exec, s[4:5]
	s_barrier
	s_cbranch_vccz .LBB0_1184
	v_mbcnt_lo_u32_b32 v0, -1, 0
	v_mbcnt_hi_u32_b32 v0, -1, v0
	s_nop 0
	v_cmp_eq_u32_e32 vcc, 0, v0
	s_and_saveexec_b64 s[36:37], vcc
	s_cbranch_execz .LBB0_1183
	v_readlane_b32 s4, v255, 52
	s_waitcnt vmcnt(0) expcnt(0) lgkmcnt(0)
	s_nop 0
	v_mov_b32_e32 v0, s4
	ds_read_b32 v3, v0
	v_readlane_b32 s4, v255, 53
	s_waitcnt lgkmcnt(0)
	v_cmp_ne_u32_e32 vcc, 0, v3
	v_mov_b32_e32 v0, s4
	ds_read_b32 v2, v0
	s_cbranch_vccnz .LBB0_1147
	v_readlane_b32 s6, v254, 8
	v_readlane_b32 s7, v254, 9
	s_load_dwordx2 s[4:5], s[6:7], 0x4
	s_mov_b32 s9, 1
	s_waitcnt lgkmcnt(0)
	s_mul_i32 s8, s4, s79
	s_mul_i32 s8, s8, s5
	s_branch .LBB0_1135
